# norm phase hbuf stores write-through (sc1) so the grid barrier's L2 write-back has nothing left to flush
# baseline (speedup 1.0000x reference)
.LBB0_204:
	v_lshl_add_u64 v[64:65], v[44:45], 0, s[8:9]
	global_load_dwordx4 v[70:73], v[64:65], off nt
	global_load_dwordx4 v[74:77], v[64:65], off offset:1024 nt
	global_load_dwordx4 v[78:81], v[64:65], off offset:2048 nt
	global_load_dwordx4 v[82:85], v[64:65], off offset:3072 nt
	v_ashrrev_i32_e32 v63, 31, v62
	v_lshlrev_b64 v[104:105], 12, v[62:63]
	v_lshl_add_u64 v[104:105], v[18:19], 0, v[104:105]
	global_load_dwordx4 v[112:115], v[104:105], off nt
	global_load_dwordx4 v[116:119], v[104:105], off offset:1024 nt
	global_load_dwordx4 v[120:123], v[104:105], off offset:2048 nt
	global_load_dwordx4 v[124:127], v[104:105], off offset:3072 nt
	s_add_u32 s8, s8, 0x2000
	s_addc_u32 s9, s9, 0
	s_cmpk_eq_u32 s8, 0x8000
	s_waitcnt vmcnt(7)
	v_mov_b32_e32 v108, v71
	s_waitcnt vmcnt(6)
	v_mov_b32_e32 v109, v75
	v_mov_b32_e32 v106, v70
	v_mov_b32_e32 v107, v74
	v_pk_mul_f32 v[108:109], v[108:109], v[108:109]
	s_nop 0
	v_pk_fma_f32 v[106:107], v[106:107], v[106:107], v[108:109]
	v_mov_b32_e32 v108, v72
	v_mov_b32_e32 v109, v76
	v_pk_fma_f32 v[106:107], v[108:109], v[108:109], v[106:107]
	v_mov_b32_e32 v108, v73
	v_mov_b32_e32 v109, v77
	v_pk_fma_f32 v[86:87], v[108:109], v[108:109], v[106:107]
	v_add_f32_e32 v33, v86, v87
	v_and_b32_e32 v87, 0x3ffffff, v43
	s_waitcnt vmcnt(5)
	v_mov_b32_e32 v88, v79
	s_waitcnt vmcnt(4)
	v_mov_b32_e32 v89, v83
	v_mov_b32_e32 v64, v78
	v_mov_b32_e32 v65, v82
	v_pk_mul_f32 v[88:89], v[88:89], v[88:89]
	s_nop 0
	v_pk_fma_f32 v[64:65], v[64:65], v[64:65], v[88:89]
	v_mov_b32_e32 v88, v80
	v_mov_b32_e32 v89, v84
	v_pk_fma_f32 v[64:65], v[88:89], v[88:89], v[64:65]
	v_mov_b32_e32 v88, v81
	v_mov_b32_e32 v89, v85
	v_pk_fma_f32 v[64:65], v[88:89], v[88:89], v[64:65]
	s_nop 0
	v_add_f32_e32 v33, v33, v64
	v_add_f32_e32 v33, v33, v65
	ds_bpermute_b32 v37, v27, v33
	s_waitcnt lgkmcnt(0)
	v_add_f32_e32 v33, v33, v37
	ds_bpermute_b32 v37, v29, v33
	s_waitcnt lgkmcnt(0)
	v_add_f32_e32 v33, v33, v37
	ds_bpermute_b32 v37, v31, v33
	s_waitcnt lgkmcnt(0)
	v_add_f32_e32 v33, v33, v37
	ds_bpermute_b32 v37, v66, v33
	s_waitcnt lgkmcnt(0)
	v_add_f32_e32 v33, v33, v37
	ds_bpermute_b32 v37, v67, v33
	s_waitcnt lgkmcnt(0)
	v_add_f32_e32 v33, v33, v37
	ds_bpermute_b32 v37, v68, v33
	s_waitcnt lgkmcnt(0)
	v_add_f32_e32 v33, v33, v37
	v_fmamk_f32 v33, v33, 0x3a800000, v202
	v_cmp_gt_f32_e32 vcc, s74, v33
	v_mul_f32_e32 v37, 0x4b800000, v33
	s_nop 0
	v_cndmask_b32_e32 v33, v33, v37, vcc
	v_rsq_f32_e32 v33, v33
	s_nop 0
	v_mul_f32_e32 v37, 0x45800000, v33
	v_cndmask_b32_e32 v64, v33, v37, vcc
	v_and_b32_e32 v33, 0xffffffe0, v42
	v_pk_mul_f32 v[70:71], v[70:71], v[64:65] op_sel_hi:[1,0]
	v_pk_mul_f32 v[72:73], v[72:73], v[64:65] op_sel_hi:[1,0]
	v_pk_fma_f32 v[70:71], v[48:49], v[70:71], v[2:3]
	v_pk_fma_f32 v[72:73], v[46:47], v[72:73], v[4:5]
	v_or_b32_e32 v86, v33, v24
	v_cvt_pk_bf16_f32 v70, v70, v71
	v_cvt_pk_bf16_f32 v71, v72, v73
	v_lshlrev_b64 v[72:73], 7, v[86:87]
	v_lshl_add_u64 v[72:73], v[20:21], 0, v[72:73]
	global_store_dwordx2 v[72:73], v[70:71], off sc1
	v_pk_mul_f32 v[70:71], v[74:75], v[64:65] op_sel_hi:[1,0]
	v_pk_mul_f32 v[72:73], v[76:77], v[64:65] op_sel_hi:[1,0]
	v_pk_fma_f32 v[70:71], v[52:53], v[70:71], v[6:7]
	v_pk_fma_f32 v[72:73], v[50:51], v[72:73], v[8:9]
	v_or_b32_e32 v86, v33, v26
	v_cvt_pk_bf16_f32 v70, v70, v71
	v_cvt_pk_bf16_f32 v71, v72, v73
	v_lshlrev_b64 v[72:73], 7, v[86:87]
	v_lshl_add_u64 v[72:73], v[20:21], 0, v[72:73]
	global_store_dwordx2 v[72:73], v[70:71], off sc1
	v_pk_mul_f32 v[70:71], v[78:79], v[64:65] op_sel_hi:[1,0]
	v_pk_mul_f32 v[72:73], v[80:81], v[64:65] op_sel_hi:[1,0]
	v_pk_fma_f32 v[70:71], v[56:57], v[70:71], v[10:11]
	v_pk_fma_f32 v[72:73], v[54:55], v[72:73], v[12:13]
	v_or_b32_e32 v86, v33, v28
	v_cvt_pk_bf16_f32 v70, v70, v71
	v_cvt_pk_bf16_f32 v71, v72, v73
	v_lshlrev_b64 v[72:73], 7, v[86:87]
	v_lshl_add_u64 v[72:73], v[20:21], 0, v[72:73]
	global_store_dwordx2 v[72:73], v[70:71], off sc1
	v_pk_mul_f32 v[70:71], v[82:83], v[64:65] op_sel_hi:[1,0]
	v_pk_mul_f32 v[64:65], v[84:85], v[64:65] op_sel_hi:[1,0]
	v_pk_fma_f32 v[70:71], v[60:61], v[70:71], v[14:15]
	v_pk_fma_f32 v[64:65], v[58:59], v[64:65], v[16:17]
	v_or_b32_e32 v86, v33, v30
	v_cvt_pk_bf16_f32 v70, v70, v71
	v_cvt_pk_bf16_f32 v71, v64, v65
	v_lshlrev_b64 v[64:65], 7, v[86:87]
	v_lshl_add_u64 v[64:65], v[20:21], 0, v[64:65]
	global_store_dwordx2 v[64:65], v[70:71], off sc1
	v_lshl_add_u64 v[42:43], v[42:43], 0, 32
	s_waitcnt vmcnt(7)
	v_mov_b32_e32 v108, v113
	s_waitcnt vmcnt(6)
	v_mov_b32_e32 v109, v117
	v_mov_b32_e32 v106, v112
	v_mov_b32_e32 v107, v116
	v_pk_mul_f32 v[108:109], v[108:109], v[108:109]
	s_nop 0
	v_pk_fma_f32 v[106:107], v[106:107], v[106:107], v[108:109]
	v_mov_b32_e32 v108, v114
	v_mov_b32_e32 v109, v118
	v_pk_fma_f32 v[106:107], v[108:109], v[108:109], v[106:107]
	v_mov_b32_e32 v108, v115
	v_mov_b32_e32 v109, v119
	v_pk_fma_f32 v[86:87], v[108:109], v[108:109], v[106:107]
	v_add_f32_e32 v33, v86, v87
	v_lshlrev_b64 v[86:87], 4, v[62:63]
	v_and_b32_e32 v87, 0x3ffffff, v87
	v_add_u32_e32 v62, 2, v62
	s_waitcnt vmcnt(5)
	v_mov_b32_e32 v88, v121
	s_waitcnt vmcnt(4)
	v_mov_b32_e32 v89, v125
	v_mov_b32_e32 v64, v120
	v_mov_b32_e32 v65, v124
	v_pk_mul_f32 v[88:89], v[88:89], v[88:89]
	s_nop 0
	v_pk_fma_f32 v[64:65], v[64:65], v[64:65], v[88:89]
	v_mov_b32_e32 v88, v122
	v_mov_b32_e32 v89, v126
	v_pk_fma_f32 v[64:65], v[88:89], v[88:89], v[64:65]
	v_mov_b32_e32 v88, v123
	v_mov_b32_e32 v89, v127
	v_pk_fma_f32 v[64:65], v[88:89], v[88:89], v[64:65]
	s_nop 0
	v_add_f32_e32 v33, v33, v64
	v_add_f32_e32 v33, v33, v65
	ds_bpermute_b32 v37, v27, v33
	s_waitcnt lgkmcnt(0)
	v_add_f32_e32 v33, v33, v37
	ds_bpermute_b32 v37, v29, v33
	s_waitcnt lgkmcnt(0)
	v_add_f32_e32 v33, v33, v37
	ds_bpermute_b32 v37, v31, v33
	s_waitcnt lgkmcnt(0)
	v_add_f32_e32 v33, v33, v37
	ds_bpermute_b32 v37, v66, v33
	s_waitcnt lgkmcnt(0)
	v_add_f32_e32 v33, v33, v37
	ds_bpermute_b32 v37, v67, v33
	s_waitcnt lgkmcnt(0)
	v_add_f32_e32 v33, v33, v37
	ds_bpermute_b32 v37, v68, v33
	s_waitcnt lgkmcnt(0)
	v_add_f32_e32 v33, v33, v37
	v_fmamk_f32 v33, v33, 0x3a800000, v202
	v_cmp_gt_f32_e32 vcc, s74, v33
	v_mul_f32_e32 v37, 0x4b800000, v33
	s_nop 0
	v_cndmask_b32_e32 v33, v33, v37, vcc
	v_rsq_f32_e32 v33, v33
	s_nop 0
	v_mul_f32_e32 v37, 0x45800000, v33
	v_cndmask_b32_e32 v64, v33, v37, vcc
	v_and_b32_e32 v33, 0xffffffe0, v86
	v_pk_mul_f32 v[112:113], v[112:113], v[64:65] op_sel_hi:[1,0]
	v_pk_mul_f32 v[114:115], v[114:115], v[64:65] op_sel_hi:[1,0]
	v_pk_fma_f32 v[112:113], v[48:49], v[112:113], v[2:3]
	v_pk_fma_f32 v[114:115], v[46:47], v[114:115], v[4:5]
	v_or_b32_e32 v86, v33, v24
	v_cvt_pk_bf16_f32 v112, v112, v113
	v_cvt_pk_bf16_f32 v113, v114, v115
	v_lshlrev_b64 v[114:115], 7, v[86:87]
	v_lshl_add_u64 v[114:115], v[20:21], 0, v[114:115]
	global_store_dwordx2 v[114:115], v[112:113], off offset:64 sc1
	v_pk_mul_f32 v[112:113], v[116:117], v[64:65] op_sel_hi:[1,0]
	v_pk_mul_f32 v[114:115], v[118:119], v[64:65] op_sel_hi:[1,0]
	v_pk_fma_f32 v[112:113], v[52:53], v[112:113], v[6:7]
	v_pk_fma_f32 v[114:115], v[50:51], v[114:115], v[8:9]
	v_or_b32_e32 v86, v33, v26
	v_cvt_pk_bf16_f32 v112, v112, v113
	v_cvt_pk_bf16_f32 v113, v114, v115
	v_lshlrev_b64 v[114:115], 7, v[86:87]
	v_lshl_add_u64 v[114:115], v[20:21], 0, v[114:115]
	global_store_dwordx2 v[114:115], v[112:113], off offset:64 sc1
	v_pk_mul_f32 v[112:113], v[120:121], v[64:65] op_sel_hi:[1,0]
	v_pk_mul_f32 v[114:115], v[122:123], v[64:65] op_sel_hi:[1,0]
	v_pk_fma_f32 v[112:113], v[56:57], v[112:113], v[10:11]
	v_pk_fma_f32 v[114:115], v[54:55], v[114:115], v[12:13]
	v_or_b32_e32 v86, v33, v28
	v_cvt_pk_bf16_f32 v112, v112, v113
	v_cvt_pk_bf16_f32 v113, v114, v115
	v_lshlrev_b64 v[114:115], 7, v[86:87]
	v_lshl_add_u64 v[114:115], v[20:21], 0, v[114:115]
	global_store_dwordx2 v[114:115], v[112:113], off offset:64 sc1
	v_pk_mul_f32 v[112:113], v[124:125], v[64:65] op_sel_hi:[1,0]
	v_pk_mul_f32 v[64:65], v[126:127], v[64:65] op_sel_hi:[1,0]
	v_pk_fma_f32 v[112:113], v[60:61], v[112:113], v[14:15]
	v_pk_fma_f32 v[64:65], v[58:59], v[64:65], v[16:17]
	v_or_b32_e32 v86, v33, v30
	v_cvt_pk_bf16_f32 v112, v112, v113
	v_cvt_pk_bf16_f32 v113, v64, v65
	v_lshlrev_b64 v[64:65], 7, v[86:87]
	v_lshl_add_u64 v[64:65], v[20:21], 0, v[64:65]
	global_store_dwordx2 v[64:65], v[112:113], off offset:64 sc1
	s_cbranch_scc0 .LBB0_204
	v_add_u32_e32 v25, s86, v25
	s_movk_i32 s8, 0x7ff
	v_cmp_lt_i32_e32 vcc, s8, v25
	v_add_u32_e32 v69, s85, v69
	s_or_b64 s[6:7], vcc, s[6:7]
	v_add_u32_e32 v32, s85, v32
	s_andn2_b64 exec, exec, s[6:7]
	s_cbranch_execnz .LBB0_203
	s_branch .LBB0_198
